# diff-latent loop: priority 3 only while issuing the loop-top K reads and next-tile global prefetch, 0 for the rest; fillers at 3
# speedup vs baseline: 1.0026x; 1.0026x over previous
.LBB0_431:
	s_setprio 0
	s_bitcmp1_b32 s18, 0
	s_cselect_b32 s4, 0x4800, 0
	v_or_b32_e32 v0, s4, v166
	v_add_u32_e32 v210, v0, v171
	s_mov_b32 s5, 0xff800000
	s_waitcnt lgkmcnt(1)
	v_mfma_f32_32x32x16_bf16 v[96:111], v[4:7], v[112:115], 0
	ds_read_b128 v[4:7], v210 offset:4608
	s_waitcnt lgkmcnt(1)
	v_mfma_f32_32x32x16_bf16 v[96:111], v[8:11], v[116:119], v[96:111]
	s_waitcnt lgkmcnt(0)
	v_mfma_f32_32x32x16_bf16 v[80:95], v[4:7], v[112:115], 0
	ds_read_b128 v[4:7], v210 offset:4640
	ds_read_b128 v[244:247], v210 offset:64
	ds_read_b128 v[214:217], v210 offset:96
	ds_read_b128 v[228:231], v210 offset:4672
	v_add3_u32 v248, s4, v235, v171
	v_add_u32_e32 v249, 0x3000, v248
	v_add_u32_e32 v248, 0x2000, v248
	ds_read2_b64 v[144:147], v249 offset0:196 offset1:198
	ds_read2_b64 v[148:151], v248 offset0:136 offset1:138
	ds_read2_b64 v[152:155], v249 offset0:200 offset1:202
	ds_read2_b64 v[156:159], v248 offset0:140 offset1:142
	ds_read2_b64 v[160:163], v249 offset0:204 offset1:206
	s_nop 8
	v_max3_f32 v0, v96, s5, v97
	v_max3_f32 v0, v0, v98, v99
	v_max3_f32 v0, v0, v100, v101
	v_max3_f32 v0, v0, v102, v103
	v_max3_f32 v0, v0, v104, v105
	v_max3_f32 v0, v0, v106, v107
	s_waitcnt lgkmcnt(8)
	v_mfma_f32_32x32x16_bf16 v[80:95], v[4:7], v[116:119], v[80:95]
	v_max3_f32 v0, v0, v108, v109
	v_max3_f32 v0, v0, v110, v111
	s_nop 9
	v_max3_f32 v0, v0, v80, v81
	v_max3_f32 v0, v0, v82, v83
	v_max3_f32 v0, v0, v84, v85
	v_max3_f32 v0, v0, v86, v87
	v_max3_f32 v0, v0, v88, v89
	v_max3_f32 v0, v0, v90, v91
	v_max3_f32 v0, v0, v92, v93
	v_max3_f32 v0, v0, v94, v95
	v_mul_f32_e32 v0, 0x3e8293ee, v0
	v_mov_b32_e32 v3, v0
	s_nop 1
	v_permlane32_swap_b32_e32 v3, v0
	s_nop 0
	v_max3_f32 v0, v2, v0, v3
	v_sub_f32_e32 v3, v2, v0
	v_exp_f32_e32 v14, v3
	v_cmp_neq_f32_e32 vcc, v0, v2
	s_cbranch_vccz .LBB0_433
	v_pk_mul_f32 v[62:63], v[62:63], v[14:15] op_sel_hi:[1,0]
	v_pk_mul_f32 v[60:61], v[60:61], v[14:15] op_sel_hi:[1,0]
	v_pk_mul_f32 v[58:59], v[58:59], v[14:15] op_sel_hi:[1,0]
	v_pk_mul_f32 v[56:57], v[56:57], v[14:15] op_sel_hi:[1,0]
	v_pk_mul_f32 v[54:55], v[54:55], v[14:15] op_sel_hi:[1,0]
	v_pk_mul_f32 v[52:53], v[52:53], v[14:15] op_sel_hi:[1,0]
	v_pk_mul_f32 v[50:51], v[50:51], v[14:15] op_sel_hi:[1,0]
	v_pk_mul_f32 v[48:49], v[48:49], v[14:15] op_sel_hi:[1,0]
	v_pk_mul_f32 v[30:31], v[30:31], v[14:15] op_sel_hi:[1,0]
	v_pk_mul_f32 v[28:29], v[28:29], v[14:15] op_sel_hi:[1,0]
	v_pk_mul_f32 v[26:27], v[26:27], v[14:15] op_sel_hi:[1,0]
	v_pk_mul_f32 v[24:25], v[24:25], v[14:15] op_sel_hi:[1,0]
	v_pk_mul_f32 v[22:23], v[22:23], v[14:15] op_sel_hi:[1,0]
	v_pk_mul_f32 v[20:21], v[20:21], v[14:15] op_sel_hi:[1,0]
	v_pk_mul_f32 v[18:19], v[18:19], v[14:15] op_sel_hi:[1,0]
	v_pk_mul_f32 v[16:17], v[16:17], v[14:15] op_sel_hi:[1,0]
